# v26
# baseline (speedup 1.0000x reference)
; DEVI void attn_unit(const Params& p, char* lds, int au) {
;     ...
;     float lmx[2];
; #pragma unroll
;     for (int qb = 0; qb < 2; ++qb) {
;       float m2 = fmaxf(fmaxf(sc[0][qb][0], sc[0][qb][1]), fmaxf(sc[0][qb][2], sc[0][qb][3]));
; #pragma unroll
;       for (int kb = 1; kb < 4; ++kb)
;         m2 = fmaxf(m2, fmaxf(fmaxf(sc[kb][qb][0], sc[kb][qb][1]), fmaxf(sc[kb][qb][2], sc[kb][qb][3])));
;       lmx[qb] = m2;
;     }
;     const bool first = (i == 0);
;     if (__any(first || (i == 1 && ((lmx[0] > 0.f) || (lmx[1] > 0.f))) || (lmx[0] > 6.f) || (lmx[1] > 6.f))) {
; #pragma unroll
;       for (int qb = 0; qb < 2; ++qb) {
;         float m2 = lmx[qb];
;         m2 = fmaxf(m2, __shfl_xor(m2, 16));
;         m2 = fmaxf(m2, __shfl_xor(m2, 32));
;         const float d = first ? m2 : fmaxf(m2, 0.f);
;         const float alpha = first ? 0.f : __builtin_amdgcn_exp2f(-d);
;         mrun[qb] += d;
;         lsum[qb] *= alpha;
; #pragma unroll
;         for (int db = 0; db < 8; ++db) o[db][qb] *= alpha;
; #pragma unroll
;         for (int kb = 0; kb < 4; ++kb) sc[kb][qb] -= d;
;       }
;     }
.LBB0_215:
	s_or_b64 exec, exec, s[2:3]
	v_lshl_or_b32 v162, s15, 14, v185
	v_add_u32_e32 v163, v162, v183
	v_add_u32_e32 v162, v162, v184
	ds_read_b128 v[168:171], v163 offset:32768
	ds_read_b128 v[186:189], v163 offset:34816
	ds_read_b128 v[198:201], v163 offset:36864
	ds_read_b128 v[202:205], v163 offset:38912
	ds_read_b128 v[190:193], v162 offset:32768
	ds_read_b128 v[194:197], v162 offset:34816
	ds_read_b128 v[206:209], v162 offset:36864
	ds_read_b128 v[210:213], v162 offset:38912
	v_max3_f32 v147, v90, v91, v92
	v_max3_f32 v146, v110, v111, v112
	v_max3_f32 v147, v147, v93, v118
	v_max3_f32 v146, v146, v113, v106
	v_max3_f32 v147, v147, v119, v120
	v_max3_f32 v146, v146, v107, v108
	v_max3_f32 v147, v147, v121, v98
	v_max3_f32 v146, v146, v109, v102
	v_max3_f32 v147, v147, v99, v100
	v_max3_f32 v146, v146, v103, v104
	v_max3_f32 v147, v147, v101, v114
	v_max3_f32 v146, v146, v105, v94
	v_max3_f32 v147, v147, v115, v116
	v_max3_f32 v146, v146, v95, v96
	v_max_f32_e32 v147, v147, v117
	v_max_f32_e32 v146, v146, v97
	v_max_f32_e32 v148, v146, v147
	s_mov_b32 s2, 0x40c00000
	v_cmp_lt_f32_e32 vcc, s2, v148
	s_cbranch_vccz .LBB0_217
	ds_bpermute_b32 v148, v123, v147
	v_max_f32_e32 v147, v147, v147
	s_waitcnt lgkmcnt(0)
	v_max_f32_e32 v148, v148, v148
	v_max_f32_e32 v147, v147, v148
	ds_bpermute_b32 v148, v125, v147
	s_waitcnt lgkmcnt(0)
	v_max3_f32 v147, v147, v148, 0
	v_exp_f32_e64 v148, -v147
	v_sub_f32_e32 v90, v90, v147
	v_sub_f32_e32 v91, v91, v147
	v_sub_f32_e32 v92, v92, v147
	v_pk_mul_f32 v[138:139], v[138:139], v[148:149] op_sel_hi:[1,0]
	v_pk_mul_f32 v[136:137], v[136:137], v[148:149] op_sel_hi:[1,0]
	v_pk_mul_f32 v[84:85], v[84:85], v[148:149] op_sel_hi:[1,0]
	v_pk_mul_f32 v[82:83], v[82:83], v[148:149] op_sel_hi:[1,0]
	v_pk_mul_f32 v[76:77], v[76:77], v[148:149] op_sel_hi:[1,0]
	v_pk_mul_f32 v[74:75], v[74:75], v[148:149] op_sel_hi:[1,0]
	v_pk_mul_f32 v[68:69], v[68:69], v[148:149] op_sel_hi:[1,0]
	v_pk_mul_f32 v[66:67], v[66:67], v[148:149] op_sel_hi:[1,0]
	v_pk_mul_f32 v[56:57], v[56:57], v[148:149] op_sel_hi:[1,0]
	v_pk_mul_f32 v[54:55], v[54:55], v[148:149] op_sel_hi:[1,0]
	v_pk_mul_f32 v[48:49], v[48:49], v[148:149] op_sel_hi:[1,0]
	v_pk_mul_f32 v[46:47], v[46:47], v[148:149] op_sel_hi:[1,0]
	v_pk_mul_f32 v[40:41], v[40:41], v[148:149] op_sel_hi:[1,0]
	v_pk_mul_f32 v[38:39], v[38:39], v[148:149] op_sel_hi:[1,0]
	v_pk_mul_f32 v[32:33], v[32:33], v[148:149] op_sel_hi:[1,0]
	v_pk_mul_f32 v[30:31], v[30:31], v[148:149] op_sel_hi:[1,0]
	v_pk_mul_f32 v[24:25], v[24:25], v[148:149] op_sel_hi:[1,0]
	v_pk_mul_f32 v[22:23], v[22:23], v[148:149] op_sel_hi:[1,0]
	ds_bpermute_b32 v148, v123, v146
	v_max_f32_e32 v146, v146, v146
	v_sub_f32_e32 v93, v93, v147
	v_sub_f32_e32 v118, v118, v147
	v_sub_f32_e32 v119, v119, v147
	s_waitcnt lgkmcnt(0)
	v_max_f32_e32 v148, v148, v148
	v_max_f32_e32 v146, v146, v148
	ds_bpermute_b32 v148, v125, v146
	v_sub_f32_e32 v120, v120, v147
	v_sub_f32_e32 v121, v121, v147
	v_sub_f32_e32 v98, v98, v147
	v_sub_f32_e32 v99, v99, v147
	s_waitcnt lgkmcnt(0)
	v_max3_f32 v146, v146, v148, 0
	v_exp_f32_e64 v148, -v146
	v_sub_f32_e32 v100, v100, v147
	v_sub_f32_e32 v101, v101, v147
	v_sub_f32_e32 v114, v114, v147
	v_sub_f32_e32 v115, v115, v147
	v_sub_f32_e32 v116, v116, v147
	v_sub_f32_e32 v117, v117, v147
	v_pk_add_f32 v[134:135], v[134:135], v[146:147]
	v_pk_mul_f32 v[142:143], v[142:143], v[148:149] op_sel_hi:[1,0]
	v_pk_mul_f32 v[140:141], v[140:141], v[148:149] op_sel_hi:[1,0]
	v_pk_mul_f32 v[80:81], v[80:81], v[148:149] op_sel_hi:[1,0]
	v_pk_mul_f32 v[78:79], v[78:79], v[148:149] op_sel_hi:[1,0]
	v_pk_mul_f32 v[72:73], v[72:73], v[148:149] op_sel_hi:[1,0]
	v_pk_mul_f32 v[70:71], v[70:71], v[148:149] op_sel_hi:[1,0]
	v_pk_mul_f32 v[60:61], v[60:61], v[148:149] op_sel_hi:[1,0]
	v_pk_mul_f32 v[58:59], v[58:59], v[148:149] op_sel_hi:[1,0]
	v_pk_mul_f32 v[52:53], v[52:53], v[148:149] op_sel_hi:[1,0]
	v_pk_mul_f32 v[50:51], v[50:51], v[148:149] op_sel_hi:[1,0]
	v_pk_mul_f32 v[44:45], v[44:45], v[148:149] op_sel_hi:[1,0]
	v_pk_mul_f32 v[42:43], v[42:43], v[148:149] op_sel_hi:[1,0]
	v_pk_mul_f32 v[36:37], v[36:37], v[148:149] op_sel_hi:[1,0]
	v_pk_mul_f32 v[34:35], v[34:35], v[148:149] op_sel_hi:[1,0]
	v_pk_mul_f32 v[28:29], v[28:29], v[148:149] op_sel_hi:[1,0]
	v_pk_mul_f32 v[26:27], v[26:27], v[148:149] op_sel_hi:[1,0]
	v_pk_mul_f32 v[4:5], v[4:5], v[148:149] op_sel_hi:[1,0]
	v_pk_mul_f32 v[2:3], v[2:3], v[148:149] op_sel_hi:[1,0]
	v_sub_f32_e32 v110, v110, v146
	v_sub_f32_e32 v111, v111, v146
	v_sub_f32_e32 v112, v112, v146
	v_sub_f32_e32 v113, v113, v146
	v_sub_f32_e32 v106, v106, v146
	v_sub_f32_e32 v107, v107, v146
	v_sub_f32_e32 v108, v108, v146
	v_sub_f32_e32 v109, v109, v146
	v_sub_f32_e32 v102, v102, v146
	v_sub_f32_e32 v103, v103, v146
	v_sub_f32_e32 v104, v104, v146
	v_sub_f32_e32 v105, v105, v146
	v_sub_f32_e32 v94, v94, v146
	v_sub_f32_e32 v95, v95, v146
	v_sub_f32_e32 v96, v96, v146
	v_sub_f32_e32 v97, v97, v146
; DEVI void attn_unit(const Params& p, char* lds, int au) {
;     ...
; #pragma unroll
;     for (int qb = 0; qb < 2; ++qb) {
;       u32x4 t0, t1;
; #pragma unroll
;       for (int kb = 0; kb < 4; ++kb) {
;         f32x4 e;
;         e[0] = __builtin_amdgcn_exp2f(sc[kb][qb][0]);
;         e[1] = __builtin_amdgcn_exp2f(sc[kb][qb][1]);
;         e[2] = __builtin_amdgcn_exp2f(sc[kb][qb][2]);
;         e[3] = __builtin_amdgcn_exp2f(sc[kb][qb][3]);
;         lsum[qb] += e;
;         uint32_t w0 = pk2(e[0], e[1]), w1 = pk2(e[2], e[3]);
;         if (kb == 0) { t0[0] = w0; t0[1] = w1; }
;         if (kb == 1) { t0[2] = w0; t0[3] = w1; }
;         if (kb == 2) { t1[0] = w0; t1[1] = w1; }
;         if (kb == 3) { t1[2] = w0; t1[3] = w1; }
;       }
;       pf[qb][0] = __builtin_bit_cast(bf16x8, t0);
;       pf[qb][1] = __builtin_bit_cast(bf16x8, t1);
;     }
;     if (!typeB) PVSTEP(lds + 32768 + vcur * 16384);
.LBB0_217:
	v_exp_f32_e32 v146, v90
	v_exp_f32_e32 v147, v91
	v_exp_f32_e32 v148, v92
	v_exp_f32_e32 v149, v93
	v_exp_f32_e32 v118, v118
	v_exp_f32_e32 v119, v119
	v_exp_f32_e32 v120, v120
	v_exp_f32_e32 v121, v121
	v_exp_f32_e32 v150, v98
	v_exp_f32_e32 v151, v99
	v_exp_f32_e32 v152, v100
	v_exp_f32_e32 v153, v101
	v_exp_f32_e32 v114, v114
	v_exp_f32_e32 v115, v115
	v_exp_f32_e32 v116, v116
	v_exp_f32_e32 v117, v117
	v_exp_f32_e32 v154, v110
	v_exp_f32_e32 v155, v111
	v_exp_f32_e32 v156, v112
	v_exp_f32_e32 v157, v113
	v_exp_f32_e32 v106, v106
	v_exp_f32_e32 v107, v107
	v_exp_f32_e32 v108, v108
	v_exp_f32_e32 v109, v109
	v_exp_f32_e32 v158, v102
	v_exp_f32_e32 v159, v103
	v_exp_f32_e32 v160, v104
	v_exp_f32_e32 v161, v105
	v_exp_f32_e32 v94, v94
	v_exp_f32_e32 v95, v95
	v_exp_f32_e32 v96, v96
	v_exp_f32_e32 v97, v97
	v_cvt_pk_bf16_f32 v90, v146, v147
	v_cvt_pk_bf16_f32 v91, v148, v149
	v_cvt_pk_bf16_f32 v92, v118, v119
	v_cvt_pk_bf16_f32 v93, v120, v121
	v_cvt_pk_bf16_f32 v98, v150, v151
	v_cvt_pk_bf16_f32 v99, v152, v153
	v_cvt_pk_bf16_f32 v100, v114, v115
	v_cvt_pk_bf16_f32 v101, v116, v117
	v_cvt_pk_bf16_f32 v110, v154, v155
	v_cvt_pk_bf16_f32 v111, v156, v157
	v_cvt_pk_bf16_f32 v112, v106, v107
	v_cvt_pk_bf16_f32 v113, v108, v109
	v_cvt_pk_bf16_f32 v102, v158, v159
	v_cvt_pk_bf16_f32 v103, v160, v161
	v_cvt_pk_bf16_f32 v104, v94, v95
	s_and_b64 vcc, exec, s[12:13]
	v_cvt_pk_bf16_f32 v105, v96, v97
	s_cbranch_vccnz .LBB0_219
	s_waitcnt lgkmcnt(4)
	v_mfma_f32_16x16x32_bf16 v[82:85], v[168:171], v[90:93], v[82:85]
	v_mfma_f32_16x16x32_bf16 v[78:81], v[168:171], v[110:113], v[78:81]
	v_pk_add_f32 v[138:139], v[148:149], v[138:139]
	v_mfma_f32_16x16x32_bf16 v[74:77], v[186:189], v[90:93], v[74:77]
	v_mfma_f32_16x16x32_bf16 v[70:73], v[186:189], v[110:113], v[70:73]
	v_pk_add_f32 v[136:137], v[146:147], v[136:137]
	v_mfma_f32_16x16x32_bf16 v[66:69], v[198:201], v[90:93], v[66:69]
	v_mfma_f32_16x16x32_bf16 v[58:61], v[198:201], v[110:113], v[58:61]
	v_pk_add_f32 v[120:121], v[120:121], v[138:139]
	v_mfma_f32_16x16x32_bf16 v[54:57], v[202:205], v[90:93], v[54:57]
	v_mfma_f32_16x16x32_bf16 v[50:53], v[202:205], v[110:113], v[50:53]
	v_pk_add_f32 v[118:119], v[118:119], v[136:137]
	ds_read_b128 v[168:171], v163 offset:40960
	ds_read_b128 v[186:189], v163 offset:43008
	ds_read_b128 v[198:201], v163 offset:45056
	ds_read_b128 v[202:205], v163 offset:47104
	s_waitcnt lgkmcnt(4)
	v_mfma_f32_16x16x32_bf16 v[82:85], v[190:193], v[98:101], v[82:85]
	v_mfma_f32_16x16x32_bf16 v[78:81], v[190:193], v[102:105], v[78:81]
	v_pk_add_f32 v[120:121], v[152:153], v[120:121]
	v_mfma_f32_16x16x32_bf16 v[74:77], v[194:197], v[98:101], v[74:77]
	v_mfma_f32_16x16x32_bf16 v[70:73], v[194:197], v[102:105], v[70:73]
	v_pk_add_f32 v[118:119], v[150:151], v[118:119]
	v_mfma_f32_16x16x32_bf16 v[66:69], v[206:209], v[98:101], v[66:69]
	v_mfma_f32_16x16x32_bf16 v[58:61], v[206:209], v[102:105], v[58:61]
	v_pk_add_f32 v[138:139], v[116:117], v[120:121]
	v_mfma_f32_16x16x32_bf16 v[54:57], v[210:213], v[98:101], v[54:57]
	v_mfma_f32_16x16x32_bf16 v[50:53], v[210:213], v[102:105], v[50:53]
	v_pk_add_f32 v[136:137], v[114:115], v[118:119]
	ds_read_b128 v[190:193], v162 offset:40960
	ds_read_b128 v[194:197], v162 offset:43008
	ds_read_b128 v[206:209], v162 offset:45056
	ds_read_b128 v[210:213], v162 offset:47104
	s_waitcnt lgkmcnt(4)
	v_mfma_f32_16x16x32_bf16 v[46:49], v[168:171], v[90:93], v[46:49]
	v_mfma_f32_16x16x32_bf16 v[42:45], v[168:171], v[110:113], v[42:45]
	v_pk_add_f32 v[114:115], v[156:157], v[142:143]
	v_mfma_f32_16x16x32_bf16 v[38:41], v[186:189], v[90:93], v[38:41]
	v_mfma_f32_16x16x32_bf16 v[34:37], v[186:189], v[110:113], v[34:37]
	v_pk_add_f32 v[116:117], v[154:155], v[140:141]
	v_mfma_f32_16x16x32_bf16 v[30:33], v[198:201], v[90:93], v[30:33]
	v_mfma_f32_16x16x32_bf16 v[26:29], v[198:201], v[110:113], v[26:29]
	v_pk_add_f32 v[108:109], v[108:109], v[114:115]
	v_mfma_f32_16x16x32_bf16 v[22:25], v[202:205], v[90:93], v[22:25]
	v_mfma_f32_16x16x32_bf16 v[2:5], v[202:205], v[110:113], v[2:5]
	v_pk_add_f32 v[106:107], v[106:107], v[116:117]
	s_waitcnt lgkmcnt(0)
	v_mfma_f32_16x16x32_bf16 v[46:49], v[190:193], v[98:101], v[46:49]
	v_mfma_f32_16x16x32_bf16 v[42:45], v[190:193], v[102:105], v[42:45]
	v_pk_add_f32 v[108:109], v[160:161], v[108:109]
	v_mfma_f32_16x16x32_bf16 v[38:41], v[194:197], v[98:101], v[38:41]
	v_mfma_f32_16x16x32_bf16 v[34:37], v[194:197], v[102:105], v[34:37]
	v_pk_add_f32 v[106:107], v[158:159], v[106:107]
	v_mfma_f32_16x16x32_bf16 v[30:33], v[206:209], v[98:101], v[30:33]
	v_mfma_f32_16x16x32_bf16 v[26:29], v[206:209], v[102:105], v[26:29]
	v_pk_add_f32 v[140:141], v[94:95], v[106:107]
	v_mfma_f32_16x16x32_bf16 v[22:25], v[210:213], v[98:101], v[22:25]
	v_mfma_f32_16x16x32_bf16 v[2:5], v[210:213], v[102:105], v[2:5]
	v_pk_add_f32 v[142:143], v[96:97], v[108:109]
	s_branch .Lpv_done
.LBB0_219:
	v_pk_add_f32 v[138:139], v[148:149], v[138:139]
	v_pk_add_f32 v[136:137], v[146:147], v[136:137]
	v_pk_add_f32 v[120:121], v[120:121], v[138:139]
	v_pk_add_f32 v[118:119], v[118:119], v[136:137]
	v_pk_add_f32 v[120:121], v[152:153], v[120:121]
	v_pk_add_f32 v[118:119], v[150:151], v[118:119]
	v_pk_add_f32 v[138:139], v[116:117], v[120:121]
	v_pk_add_f32 v[136:137], v[114:115], v[118:119]
	v_pk_add_f32 v[114:115], v[156:157], v[142:143]
	v_pk_add_f32 v[116:117], v[154:155], v[140:141]
	v_pk_add_f32 v[108:109], v[108:109], v[114:115]
	v_pk_add_f32 v[106:107], v[106:107], v[116:117]
	v_pk_add_f32 v[108:109], v[160:161], v[108:109]
	v_pk_add_f32 v[106:107], v[158:159], v[106:107]
	v_pk_add_f32 v[140:141], v[94:95], v[106:107]
	v_pk_add_f32 v[142:143], v[96:97], v[108:109]
.Lpv_done:
	s_add_i32 s8, s8, -1
	s_add_i32 s2, s10, s14
	s_cmp_eq_u32 s2, 2
	s_waitcnt vmcnt(0)
	s_barrier
	s_cbranch_scc1 .LBB0_223
	s_mov_b32 s15, s11
	s_mov_b32 s18, s14
	s_branch .LBB0_206
